# norm items of 32 rows (528 items) in the baseline pop order, on top of hand-written norm/GEMV, async pop
# speedup vs baseline: 1.0201x; 1.0089x over previous
.LBB0_29:
	v_writelane_b32 v255, s21, 8
	v_writelane_b32 v255, s20, 9
	v_writelane_b32 v255, s16, 10
	s_nop 1
	v_writelane_b32 v255, s17, 11
	s_or_b64 exec, exec, s[4:5]
	s_movk_i32 s3, 0x130
	v_writelane_b32 v255, s18, 12
	s_and_b64 s[4:5], s[18:19], exec
	s_cselect_b32 s70, s3, 0x340
	s_add_i32 s71, s70, 0x3d0
	s_add_u32 s14, s10, 0x9000
	s_addc_u32 s15, s11, 0
	s_add_u32 s72, s10, 0x2a00000
	s_addc_u32 s73, s11, 0
	s_add_u32 s16, s10, 0x1c000
	s_addc_u32 s17, s11, 0
	v_writelane_b32 v255, s19, 13
	s_add_u32 s18, s10, 0x10000
	s_addc_u32 s19, s11, 0
	s_add_u32 s4, s10, 0x1800000
	s_addc_u32 s5, s11, 0
	v_writelane_b32 v255, s4, 14
	v_mov_b32_e32 v67, 0
	s_movk_i32 s79, 0x100
	v_writelane_b32 v255, s5, 15
	s_add_u32 s4, s10, 0xd00000
	s_addc_u32 s5, s11, 0
	v_writelane_b32 v255, s4, 16
	s_movk_i32 s80, 0xff
	v_mov_b32_e32 v68, 0x358637bd
	v_writelane_b32 v255, s5, 17
	s_add_u32 s4, s10, 0xb00000
	s_addc_u32 s5, s11, 0
	v_writelane_b32 v255, s4, 18
	s_movk_i32 s81, 0x80
	s_movk_i32 s83, 0x800
	v_writelane_b32 v255, s5, 19
	s_add_u32 s4, s10, 0x900000
	s_addc_u32 s5, s11, 0
	v_writelane_b32 v255, s4, 20
	s_movk_i32 s84, 0x1f8
	s_movk_i32 s85, 0x204
	v_writelane_b32 v255, s5, 21
	s_add_u32 s4, s10, 0x800000
	s_addc_u32 s5, s11, 0
	s_add_u32 s30, s10, 0x200000
	s_addc_u32 s31, s11, 0
	s_add_u32 s34, s10, 0x120000
	s_addc_u32 s35, s11, 0
	s_add_u32 s74, s10, 0x2200000
	s_addc_u32 s75, s11, 0
	s_add_u32 s76, s10, 0x1e00000
	v_writelane_b32 v255, s4, 22
	s_addc_u32 s77, s11, 0
	s_add_i32 s78, 0, 0x20180
	v_writelane_b32 v255, s5, 23
	s_mov_b32 s89, 0x5040100
	s_mov_b32 s97, 0x7060302
	s_mov_b32 s68, 0x2aaaaaab
	s_movk_i32 s87, 0x6000
	s_add_i32 s3, 0, 0x10000
	s_movk_i32 s86, 0x208
	s_mov_b32 s88, 0x3fb8aa3b
	s_mov_b32 s92, 0xc2ce8ed0
	s_mov_b32 s93, 0x42b17218
	s_brev_b32 s38, 18
	s_movk_i32 s39, 0xffc0
	s_mov_b32 s82, 0xfe5163ab
	s_mov_b32 s90, 0x3c439041
	s_mov_b32 s91, 0xdb629599
	s_mov_b32 s40, 0xf534ddc0
	s_mov_b32 s41, 0xfc2757d1
	s_mov_b32 s46, 0x4e441529
	s_mov_b32 s20, 0xa2f9836e
	s_mov_b32 s21, 0x3fc90fda
	s_mov_b32 s22, 0x3f22f983
	s_mov_b32 s23, 0xbfc90fda
	v_mov_b32_e32 v69, 0x3c0881c4
	v_mov_b32_e32 v70, 0xbab64f3b
	s_brev_b32 s24, 1
	v_mov_b32_e32 v71, 0x3ab69700
	s_add_i32 s25, 0, 0x4600
	v_mov_b32_e32 v72, s78
	v_mov_b32_e32 v73, 0x80
	v_mov_b32_e32 v74, 0x7f800000
	v_not_b32_e32 v75, 63
	v_not_b32_e32 v76, 31
	v_mov_b32_e32 v77, 0x7fc00000
	v_mov_b32_e32 v78, 0x7f000000
	s_add_i32 s26, 0, 0x8600
	s_add_i32 s27, 0, 0x410
	s_add_i32 s28, 0, 0x618
	s_mov_b64 s[48:49], 0
	s_mov_b32 s37, 0
	s_branch .LBB0_33

.LBB0_56:
	s_load_dwordx2 s[52:53], s[0:1], 0x0
	s_load_dwordx2 s[58:59], s[0:1], 0x10
	s_load_dwordx2 s[56:57], s[0:1], 0x30
	s_sub_i32 s36, s45, s70
	s_lshl_b32 s8, s36, 5
	s_lshl_b32 s9, s29, 2
	s_add_i32 s8, s8, s9
	s_mov_b32 s9, 0
	v_lshlrev_b32_e32 v66, 4, v80
	v_lshlrev_b32_e32 v82, 3, v80
	s_lshl_b64 s[64:65], s[8:9], 11
	s_add_u32 s64, s72, s64
	s_addc_u32 s65, s73, s65
	s_lshr_b32 s54, s8, 13
	s_mul_i32 s54, s54, 0x6000
	s_add_u32 s60, s18, s54
	s_addc_u32 s61, s19, 0
	s_lshl_b64 s[62:63], s[8:9], 12
	s_waitcnt lgkmcnt(0)
	s_add_u32 s62, s52, s62
	s_addc_u32 s63, s53, s63
	s_cmpk_lt_i32 s8, 0x4000
	s_cbranch_scc1 .Lnorm_lat
	s_add_i32 s54, s8, 0xffffc000
	s_mov_b32 s55, 0
	s_lshl_b64 s[62:63], s[54:55], 12
	s_add_u32 s62, s58, s62
	s_addc_u32 s63, s59, s63
	s_mov_b64 s[60:61], s[16:17]
.Lnorm_lat:
	s_add_u32 s68, s60, 0x1000
	s_addc_u32 s69, s61, 0
	global_load_dwordx4 v[2:5], v66, s[56:57]
	global_load_dwordx4 v[6:9], v66, s[56:57] offset:1024
	global_load_dwordx4 v[10:13], v66, s[56:57] offset:2048
	global_load_dwordx4 v[14:17], v66, s[56:57] offset:3072
	global_load_dwordx4 v[18:21], v66, s[68:69]
	global_load_dwordx4 v[22:25], v66, s[68:69] offset:1024
	global_load_dwordx4 v[26:29], v66, s[68:69] offset:2048
	global_load_dwordx4 v[30:33], v66, s[68:69] offset:3072
	global_load_dwordx4 v[34:37], v66, s[60:61]
	global_load_dwordx4 v[38:41], v66, s[60:61] offset:1024
	global_load_dwordx4 v[42:45], v66, s[60:61] offset:2048
	global_load_dwordx4 v[46:49], v66, s[60:61] offset:3072
	global_load_dwordx4 v[106:109], v66, s[62:63] nt
	global_load_dwordx4 v[110:113], v66, s[62:63] offset:1024 nt
	global_load_dwordx4 v[114:117], v66, s[62:63] offset:2048 nt
	global_load_dwordx4 v[118:121], v66, s[62:63] offset:3072 nt
	s_add_u32 s62, s62, 0x1000
	s_addc_u32 s63, s63, 0
	global_load_dwordx4 v[122:125], v66, s[62:63] nt
	global_load_dwordx4 v[126:129], v66, s[62:63] offset:1024 nt
	global_load_dwordx4 v[130:133], v66, s[62:63] offset:2048 nt
	global_load_dwordx4 v[134:137], v66, s[62:63] offset:3072 nt
	s_add_u32 s62, s62, 0x1000
	s_addc_u32 s63, s63, 0
	global_load_dwordx4 v[138:141], v66, s[62:63] nt
	global_load_dwordx4 v[142:145], v66, s[62:63] offset:1024 nt
	global_load_dwordx4 v[146:149], v66, s[62:63] offset:2048 nt
	global_load_dwordx4 v[150:153], v66, s[62:63] offset:3072 nt
	s_add_u32 s62, s62, 0x1000
	s_addc_u32 s63, s63, 0
	global_load_dwordx4 v[154:157], v66, s[62:63] nt
	global_load_dwordx4 v[158:161], v66, s[62:63] offset:1024 nt
	global_load_dwordx4 v[162:165], v66, s[62:63] offset:2048 nt
	global_load_dwordx4 v[166:169], v66, s[62:63] offset:3072 nt
	s_waitcnt vmcnt(20)
	v_pk_add_f32 v[18:19], v[18:19], 1.0 op_sel_hi:[1,0]
	v_pk_add_f32 v[20:21], v[20:21], 1.0 op_sel_hi:[1,0]
	v_pk_add_f32 v[22:23], v[22:23], 1.0 op_sel_hi:[1,0]
	v_pk_add_f32 v[24:25], v[24:25], 1.0 op_sel_hi:[1,0]
	v_pk_add_f32 v[26:27], v[26:27], 1.0 op_sel_hi:[1,0]
	v_pk_add_f32 v[28:29], v[28:29], 1.0 op_sel_hi:[1,0]
	v_pk_add_f32 v[30:31], v[30:31], 1.0 op_sel_hi:[1,0]
	v_pk_add_f32 v[32:33], v[32:33], 1.0 op_sel_hi:[1,0]
	v_pk_mul_f32 v[2:3], v[2:3], v[18:19]
	v_pk_mul_f32 v[4:5], v[4:5], v[20:21]
	v_pk_mul_f32 v[6:7], v[6:7], v[22:23]
	v_pk_mul_f32 v[8:9], v[8:9], v[24:25]
	v_pk_mul_f32 v[10:11], v[10:11], v[26:27]
	v_pk_mul_f32 v[12:13], v[12:13], v[28:29]
	v_pk_mul_f32 v[14:15], v[14:15], v[30:31]
	v_pk_mul_f32 v[16:17], v[16:17], v[32:33]
	s_waitcnt vmcnt(0)
	v_pk_mul_f32 v[86:87], v[106:107], v[106:107]
	v_pk_mul_f32 v[88:89], v[108:109], v[108:109]
	v_pk_mul_f32 v[90:91], v[122:123], v[122:123]
	v_pk_mul_f32 v[92:93], v[124:125], v[124:125]
	v_pk_mul_f32 v[94:95], v[138:139], v[138:139]
	v_pk_mul_f32 v[96:97], v[140:141], v[140:141]
	v_pk_mul_f32 v[98:99], v[154:155], v[154:155]
	v_pk_mul_f32 v[100:101], v[156:157], v[156:157]
	v_pk_fma_f32 v[86:87], v[110:111], v[110:111], v[86:87]
	v_pk_fma_f32 v[88:89], v[112:113], v[112:113], v[88:89]
	v_pk_fma_f32 v[90:91], v[126:127], v[126:127], v[90:91]
	v_pk_fma_f32 v[92:93], v[128:129], v[128:129], v[92:93]
	v_pk_fma_f32 v[94:95], v[142:143], v[142:143], v[94:95]
	v_pk_fma_f32 v[96:97], v[144:145], v[144:145], v[96:97]
	v_pk_fma_f32 v[98:99], v[158:159], v[158:159], v[98:99]
	v_pk_fma_f32 v[100:101], v[160:161], v[160:161], v[100:101]
	v_pk_fma_f32 v[86:87], v[114:115], v[114:115], v[86:87]
	v_pk_fma_f32 v[88:89], v[116:117], v[116:117], v[88:89]
	v_pk_fma_f32 v[90:91], v[130:131], v[130:131], v[90:91]
	v_pk_fma_f32 v[92:93], v[132:133], v[132:133], v[92:93]
	v_pk_fma_f32 v[94:95], v[146:147], v[146:147], v[94:95]
	v_pk_fma_f32 v[96:97], v[148:149], v[148:149], v[96:97]
	v_pk_fma_f32 v[98:99], v[162:163], v[162:163], v[98:99]
	v_pk_fma_f32 v[100:101], v[164:165], v[164:165], v[100:101]
	v_pk_fma_f32 v[86:87], v[118:119], v[118:119], v[86:87]
	v_pk_fma_f32 v[88:89], v[120:121], v[120:121], v[88:89]
	v_pk_fma_f32 v[90:91], v[134:135], v[134:135], v[90:91]
	v_pk_fma_f32 v[92:93], v[136:137], v[136:137], v[92:93]
	v_pk_fma_f32 v[94:95], v[150:151], v[150:151], v[94:95]
	v_pk_fma_f32 v[96:97], v[152:153], v[152:153], v[96:97]
	v_pk_fma_f32 v[98:99], v[166:167], v[166:167], v[98:99]
	v_pk_fma_f32 v[100:101], v[168:169], v[168:169], v[100:101]
	v_pk_add_f32 v[86:87], v[86:87], v[88:89]
	v_pk_add_f32 v[90:91], v[90:91], v[92:93]
	v_pk_add_f32 v[94:95], v[94:95], v[96:97]
	v_pk_add_f32 v[98:99], v[98:99], v[100:101]
	v_add_f32_e32 v50, v86, v87
	v_add_f32_e32 v51, v90, v91
	v_add_f32_e32 v52, v94, v95
	v_add_f32_e32 v53, v98, v99
	v_add_f32_dpp v50, v50, v50 quad_perm:[1,0,3,2] row_mask:0xf bank_mask:0xf
	v_add_f32_dpp v51, v51, v51 quad_perm:[1,0,3,2] row_mask:0xf bank_mask:0xf
	v_add_f32_dpp v52, v52, v52 quad_perm:[1,0,3,2] row_mask:0xf bank_mask:0xf
	v_add_f32_dpp v53, v53, v53 quad_perm:[1,0,3,2] row_mask:0xf bank_mask:0xf
	v_add_f32_dpp v50, v50, v50 quad_perm:[2,3,0,1] row_mask:0xf bank_mask:0xf
	v_add_f32_dpp v51, v51, v51 quad_perm:[2,3,0,1] row_mask:0xf bank_mask:0xf
	v_add_f32_dpp v52, v52, v52 quad_perm:[2,3,0,1] row_mask:0xf bank_mask:0xf
	v_add_f32_dpp v53, v53, v53 quad_perm:[2,3,0,1] row_mask:0xf bank_mask:0xf
	v_add_f32_dpp v50, v50, v50 row_half_mirror row_mask:0xf bank_mask:0xf
	v_add_f32_dpp v51, v51, v51 row_half_mirror row_mask:0xf bank_mask:0xf
	v_add_f32_dpp v52, v52, v52 row_half_mirror row_mask:0xf bank_mask:0xf
	v_add_f32_dpp v53, v53, v53 row_half_mirror row_mask:0xf bank_mask:0xf
	v_add_f32_dpp v50, v50, v50 row_mirror row_mask:0xf bank_mask:0xf
	v_add_f32_dpp v51, v51, v51 row_mirror row_mask:0xf bank_mask:0xf
	v_add_f32_dpp v52, v52, v52 row_mirror row_mask:0xf bank_mask:0xf
	v_add_f32_dpp v53, v53, v53 row_mirror row_mask:0xf bank_mask:0xf
	v_add_f32_dpp v50, v50, v50 row_bcast:15 row_mask:0xa bank_mask:0xf
	v_add_f32_dpp v51, v51, v51 row_bcast:15 row_mask:0xa bank_mask:0xf
	v_add_f32_dpp v52, v52, v52 row_bcast:15 row_mask:0xa bank_mask:0xf
	v_add_f32_dpp v53, v53, v53 row_bcast:15 row_mask:0xa bank_mask:0xf
	v_add_f32_dpp v50, v50, v50 row_bcast:31 row_mask:0xc bank_mask:0xf
	v_add_f32_dpp v51, v51, v51 row_bcast:31 row_mask:0xc bank_mask:0xf
	v_add_f32_dpp v52, v52, v52 row_bcast:31 row_mask:0xc bank_mask:0xf
	v_add_f32_dpp v53, v53, v53 row_bcast:31 row_mask:0xc bank_mask:0xf
	v_readlane_b32 s52, v50, 63
	v_readlane_b32 s53, v51, 63
	v_readlane_b32 s54, v52, 63
	v_readlane_b32 s55, v53, 63
	v_mov_b32_e32 v60, s52
	v_mov_b32_e32 v62, s53
	v_mov_b32_e32 v64, s54
	v_mov_b32_e32 v84, s55
	v_fmamk_f32 v60, v60, 0x3a800000, v68
	v_fmamk_f32 v62, v62, 0x3a800000, v68
	v_fmamk_f32 v64, v64, 0x3a800000, v68
	v_fmamk_f32 v84, v84, 0x3a800000, v68
	v_rsq_f32_e32 v60, v60
	v_rsq_f32_e32 v62, v62
	v_rsq_f32_e32 v64, v64
	v_rsq_f32_e32 v84, v84
	v_pk_mul_f32 v[106:107], v[60:61], v[106:107] op_sel_hi:[0,1]
	v_pk_mul_f32 v[108:109], v[60:61], v[108:109] op_sel_hi:[0,1]
	v_pk_mul_f32 v[110:111], v[60:61], v[110:111] op_sel_hi:[0,1]
	v_pk_mul_f32 v[112:113], v[60:61], v[112:113] op_sel_hi:[0,1]
	v_pk_mul_f32 v[114:115], v[60:61], v[114:115] op_sel_hi:[0,1]
	v_pk_mul_f32 v[116:117], v[60:61], v[116:117] op_sel_hi:[0,1]
	v_pk_mul_f32 v[118:119], v[60:61], v[118:119] op_sel_hi:[0,1]
	v_pk_mul_f32 v[120:121], v[60:61], v[120:121] op_sel_hi:[0,1]
	v_pk_fma_f32 v[106:107], v[106:107], v[2:3], v[34:35]
	v_pk_fma_f32 v[108:109], v[108:109], v[4:5], v[36:37]
	v_pk_fma_f32 v[110:111], v[110:111], v[6:7], v[38:39]
	v_pk_fma_f32 v[112:113], v[112:113], v[8:9], v[40:41]
	v_pk_fma_f32 v[114:115], v[114:115], v[10:11], v[42:43]
	v_pk_fma_f32 v[116:117], v[116:117], v[12:13], v[44:45]
	v_pk_fma_f32 v[118:119], v[118:119], v[14:15], v[46:47]
	v_pk_fma_f32 v[120:121], v[120:121], v[16:17], v[48:49]
	v_cvt_pk_bf16_f32 v106, v106, v107
	v_cvt_pk_bf16_f32 v107, v108, v109
	v_cvt_pk_bf16_f32 v110, v110, v111
	v_cvt_pk_bf16_f32 v111, v112, v113
	v_cvt_pk_bf16_f32 v114, v114, v115
	v_cvt_pk_bf16_f32 v115, v116, v117
	v_cvt_pk_bf16_f32 v118, v118, v119
	v_cvt_pk_bf16_f32 v119, v120, v121
	global_store_dwordx2 v82, v[106:107], s[64:65]
	global_store_dwordx2 v82, v[110:111], s[64:65] offset:512
	global_store_dwordx2 v82, v[114:115], s[64:65] offset:1024
	global_store_dwordx2 v82, v[118:119], s[64:65] offset:1536
	s_add_u32 s64, s64, 0x800
	s_addc_u32 s65, s65, 0
	v_pk_mul_f32 v[122:123], v[62:63], v[122:123] op_sel_hi:[0,1]
	v_pk_mul_f32 v[124:125], v[62:63], v[124:125] op_sel_hi:[0,1]
	v_pk_mul_f32 v[126:127], v[62:63], v[126:127] op_sel_hi:[0,1]
	v_pk_mul_f32 v[128:129], v[62:63], v[128:129] op_sel_hi:[0,1]
	v_pk_mul_f32 v[130:131], v[62:63], v[130:131] op_sel_hi:[0,1]
	v_pk_mul_f32 v[132:133], v[62:63], v[132:133] op_sel_hi:[0,1]
	v_pk_mul_f32 v[134:135], v[62:63], v[134:135] op_sel_hi:[0,1]
	v_pk_mul_f32 v[136:137], v[62:63], v[136:137] op_sel_hi:[0,1]
	v_pk_fma_f32 v[122:123], v[122:123], v[2:3], v[34:35]
	v_pk_fma_f32 v[124:125], v[124:125], v[4:5], v[36:37]
	v_pk_fma_f32 v[126:127], v[126:127], v[6:7], v[38:39]
	v_pk_fma_f32 v[128:129], v[128:129], v[8:9], v[40:41]
	v_pk_fma_f32 v[130:131], v[130:131], v[10:11], v[42:43]
	v_pk_fma_f32 v[132:133], v[132:133], v[12:13], v[44:45]
	v_pk_fma_f32 v[134:135], v[134:135], v[14:15], v[46:47]
	v_pk_fma_f32 v[136:137], v[136:137], v[16:17], v[48:49]
	v_cvt_pk_bf16_f32 v122, v122, v123
	v_cvt_pk_bf16_f32 v123, v124, v125
	v_cvt_pk_bf16_f32 v126, v126, v127
	v_cvt_pk_bf16_f32 v127, v128, v129
	v_cvt_pk_bf16_f32 v130, v130, v131
	v_cvt_pk_bf16_f32 v131, v132, v133
	v_cvt_pk_bf16_f32 v134, v134, v135
	v_cvt_pk_bf16_f32 v135, v136, v137
	global_store_dwordx2 v82, v[122:123], s[64:65]
	global_store_dwordx2 v82, v[126:127], s[64:65] offset:512
	global_store_dwordx2 v82, v[130:131], s[64:65] offset:1024
	global_store_dwordx2 v82, v[134:135], s[64:65] offset:1536
	s_add_u32 s64, s64, 0x800
	s_addc_u32 s65, s65, 0
	v_pk_mul_f32 v[138:139], v[64:65], v[138:139] op_sel_hi:[0,1]
	v_pk_mul_f32 v[140:141], v[64:65], v[140:141] op_sel_hi:[0,1]
	v_pk_mul_f32 v[142:143], v[64:65], v[142:143] op_sel_hi:[0,1]
	v_pk_mul_f32 v[144:145], v[64:65], v[144:145] op_sel_hi:[0,1]
	v_pk_mul_f32 v[146:147], v[64:65], v[146:147] op_sel_hi:[0,1]
	v_pk_mul_f32 v[148:149], v[64:65], v[148:149] op_sel_hi:[0,1]
	v_pk_mul_f32 v[150:151], v[64:65], v[150:151] op_sel_hi:[0,1]
	v_pk_mul_f32 v[152:153], v[64:65], v[152:153] op_sel_hi:[0,1]
	v_pk_fma_f32 v[138:139], v[138:139], v[2:3], v[34:35]
	v_pk_fma_f32 v[140:141], v[140:141], v[4:5], v[36:37]
	v_pk_fma_f32 v[142:143], v[142:143], v[6:7], v[38:39]
	v_pk_fma_f32 v[144:145], v[144:145], v[8:9], v[40:41]
	v_pk_fma_f32 v[146:147], v[146:147], v[10:11], v[42:43]
	v_pk_fma_f32 v[148:149], v[148:149], v[12:13], v[44:45]
	v_pk_fma_f32 v[150:151], v[150:151], v[14:15], v[46:47]
	v_pk_fma_f32 v[152:153], v[152:153], v[16:17], v[48:49]
	v_cvt_pk_bf16_f32 v138, v138, v139
	v_cvt_pk_bf16_f32 v139, v140, v141
	v_cvt_pk_bf16_f32 v142, v142, v143
	v_cvt_pk_bf16_f32 v143, v144, v145
	v_cvt_pk_bf16_f32 v146, v146, v147
	v_cvt_pk_bf16_f32 v147, v148, v149
	v_cvt_pk_bf16_f32 v150, v150, v151
	v_cvt_pk_bf16_f32 v151, v152, v153
	global_store_dwordx2 v82, v[138:139], s[64:65]
	global_store_dwordx2 v82, v[142:143], s[64:65] offset:512
	global_store_dwordx2 v82, v[146:147], s[64:65] offset:1024
	global_store_dwordx2 v82, v[150:151], s[64:65] offset:1536
	s_add_u32 s64, s64, 0x800
	s_addc_u32 s65, s65, 0
	v_pk_mul_f32 v[154:155], v[84:85], v[154:155] op_sel_hi:[0,1]
	v_pk_mul_f32 v[156:157], v[84:85], v[156:157] op_sel_hi:[0,1]
	v_pk_mul_f32 v[158:159], v[84:85], v[158:159] op_sel_hi:[0,1]
	v_pk_mul_f32 v[160:161], v[84:85], v[160:161] op_sel_hi:[0,1]
	v_pk_mul_f32 v[162:163], v[84:85], v[162:163] op_sel_hi:[0,1]
	v_pk_mul_f32 v[164:165], v[84:85], v[164:165] op_sel_hi:[0,1]
	v_pk_mul_f32 v[166:167], v[84:85], v[166:167] op_sel_hi:[0,1]
	v_pk_mul_f32 v[168:169], v[84:85], v[168:169] op_sel_hi:[0,1]
	v_pk_fma_f32 v[154:155], v[154:155], v[2:3], v[34:35]
	v_pk_fma_f32 v[156:157], v[156:157], v[4:5], v[36:37]
	v_pk_fma_f32 v[158:159], v[158:159], v[6:7], v[38:39]
	v_pk_fma_f32 v[160:161], v[160:161], v[8:9], v[40:41]
	v_pk_fma_f32 v[162:163], v[162:163], v[10:11], v[42:43]
	v_pk_fma_f32 v[164:165], v[164:165], v[12:13], v[44:45]
	v_pk_fma_f32 v[166:167], v[166:167], v[14:15], v[46:47]
	v_pk_fma_f32 v[168:169], v[168:169], v[16:17], v[48:49]
	v_cvt_pk_bf16_f32 v154, v154, v155
	v_cvt_pk_bf16_f32 v155, v156, v157
	v_cvt_pk_bf16_f32 v158, v158, v159
	v_cvt_pk_bf16_f32 v159, v160, v161
	v_cvt_pk_bf16_f32 v162, v162, v163
	v_cvt_pk_bf16_f32 v163, v164, v165
	v_cvt_pk_bf16_f32 v166, v166, v167
	v_cvt_pk_bf16_f32 v167, v168, v169
	global_store_dwordx2 v82, v[154:155], s[64:65]
	global_store_dwordx2 v82, v[158:159], s[64:65] offset:512
	global_store_dwordx2 v82, v[162:163], s[64:65] offset:1024
	global_store_dwordx2 v82, v[166:167], s[64:65] offset:1536
	s_add_u32 s64, s64, 0x800
	s_addc_u32 s65, s65, 0
	s_mov_b32 s68, 0x2aaaaaab
	s_mov_b64 s[52:53], 0
